# fast attention units: redundant end-of-unit workgroup barrier removed (the queue-loop head barrier follows immediately); includes the out-projection epilogue change
# baseline (speedup 1.0000x reference)
;     ...
;   __syncthreads();
; __device__ __forceinline__ void phase_attn(const Params& p, int layer, char* lds, int slot, const int wave_s) {
;     ...
;     __syncthreads();
.LBB0_536:
	s_or_b64 exec, exec, s[0:1]
	s_mov_b64 s[0:1], 0
	s_waitcnt lgkmcnt(0)


;     ...
;   __syncthreads();
; __device__ __forceinline__ void phase_attn(const Params& p, int layer, char* lds, int slot, const int wave_s) {
;     ...
;     __syncthreads();
.LBB0_574:
	s_or_b64 exec, exec, s[0:1]
	s_waitcnt lgkmcnt(0)

